# sliding-window tile loop: all K fragment LDS reads issued up front with counted waits
# speedup vs baseline: 1.0073x; 1.0024x over previous
; #define LAS __attribute__((address_space(3)))
; __device__ __forceinline__ float half_max(float m) { auto rr = __builtin_amdgcn_permlane32_swap(__float_as_uint(m), __float_as_uint(m), false, false); return fmaxf(__uint_as_float(rr[0]), __uint_as_float(rr[1])); }
; #define MFMA32(a, b, c) __builtin_amdgcn_mfma_f32_32x32x16_bf16((a), (b), (c), 0, 0, 0)
; template <int NDB>
; __device__ __forceinline__ void sm_update(f32x16& s0, f32x16& s1, float& m, float& l, f32x16 (&o)[NDB], bf16x8 (&pk)[4]) {
;     float mx = fmaxf(s0[0], s1[0]);
; #pragma unroll
;     for (int r = 1; r < 16; ++r) mx = fmaxf(mx, fmaxf(s0[r], s1[r]));
;     mx = half_max(mx);
;     const float mn = fmaxf(m, mx);
;     if (__any(mn > m)) {
; __device__ __forceinline__ void swa_unit(int b, int kvh, int qb, const bf16* U, const bf16* VTb, bf16* Y, const float* sinks, const float* qgain, const int* pos, unsigned char* lds, int wid, int lane) {
;     ...
;         for (int t = tlo; t <= thi; ++t) {
;             const LAS unsigned char* Kb = kfp + (t - T0) * 8192; const LAS unsigned char* Vb = vfp + (t - T0) * 8192;
;             f32x16 s0 = f32x16{}, s1 = f32x16{};
; #pragma unroll
;             for (int ks = 0; ks < 4; ++ks) { const bf16x8 a0 = *(const LAS bf16x8*)(Kb + kofs[ks]), a1 = *(const LAS bf16x8*)(Kb + 4096 + kofs[ks]); s0 = MFMA32(a0, qf[ks], s0); s1 = MFMA32(a1, qf[ks], s1); }
;             const int rel = tq - 64 * t - 8 * hi;
; #pragma unroll
;             for (int r = 0; r < 16; ++r) { const int key = 16 * (r >> 3) + (r & 7);
;                 if (key > rel || rel - key >= 128) s0[r] = -INFINITY;
;                 if (key + 32 > rel || rel - (key + 32) >= 128) s1[r] = -INFINITY; }
.LBB0_459:
	v_add_u32_e32 v0, s0, v136
	ds_read_b128 v[162:165], v0
	ds_read_b128 v[166:169], v0 offset:4096
	v_add_u32_e32 v0, s0, v135
	ds_read_b128 v[170:173], v0
	ds_read_b128 v[174:177], v0 offset:4096
	v_add_u32_e32 v0, s0, v134
	ds_read_b128 v[178:181], v0
	ds_read_b128 v[182:185], v0 offset:4096
	v_add_u32_e32 v0, s0, v133
	ds_read_b128 v[186:189], v0
	ds_read_b128 v[190:193], v0 offset:4096
	v_cmp_gt_u32_e32 vcc, s20, v116
	v_add_u32_e32 v2, 0xffffff60, v116
	s_waitcnt lgkmcnt(7)
	v_mfma_f32_32x32x16_bf16 v[48:63], v[162:165], v[92:95], 0
	s_waitcnt lgkmcnt(6)
	v_mfma_f32_32x32x16_bf16 v[64:79], v[166:169], v[92:95], 0
	s_waitcnt lgkmcnt(5)
	v_mfma_f32_32x32x16_bf16 v[48:63], v[170:173], v[84:87], v[48:63]
	s_waitcnt lgkmcnt(4)
	v_mfma_f32_32x32x16_bf16 v[64:79], v[174:177], v[84:87], v[64:79]
	s_waitcnt lgkmcnt(3)
	v_mfma_f32_32x32x16_bf16 v[48:63], v[178:181], v[88:91], v[48:63]
	s_waitcnt lgkmcnt(2)
	v_mfma_f32_32x32x16_bf16 v[64:79], v[182:185], v[88:91], v[64:79]
	s_waitcnt lgkmcnt(1)
	v_mfma_f32_32x32x16_bf16 v[48:63], v[186:189], v[80:83], v[48:63]
	s_waitcnt lgkmcnt(0)
	v_mfma_f32_32x32x16_bf16 v[64:79], v[190:193], v[80:83], v[64:79]
	s_nop 9
	v_cndmask_b32_e32 v0, v141, v48, vcc
	v_cmp_lt_u32_e32 vcc, s21, v2
	v_add_u32_e32 v2, 0xffffff7f, v116
	s_nop 0
	v_cndmask_b32_e32 v121, v141, v64, vcc
	v_cmp_lt_u32_e32 vcc, s21, v2
	v_add_u32_e32 v2, 0xffffff5f, v116
	s_nop 0
	v_cndmask_b32_e32 v122, v141, v49, vcc
	v_cmp_lt_u32_e32 vcc, s21, v2
	v_add_u32_e32 v2, 0xffffff7e, v116
	s_nop 0
	v_cndmask_b32_e32 v123, v141, v65, vcc
	v_cmp_lt_u32_e32 vcc, s21, v2
	v_add_u32_e32 v2, 0xffffff5e, v116
	v_max_f32_e32 v4, v123, v123
	v_cndmask_b32_e32 v117, v141, v50, vcc
	v_cmp_lt_u32_e32 vcc, s21, v2
	v_add_u32_e32 v2, 0xffffff7d, v116
	s_nop 0
	v_cndmask_b32_e32 v118, v141, v66, vcc
	v_cmp_lt_u32_e32 vcc, s21, v2
	v_add_u32_e32 v2, 0xffffff5d, v116
	s_nop 0
	v_cndmask_b32_e32 v119, v141, v51, vcc
	v_cmp_lt_u32_e32 vcc, s21, v2
	v_add_u32_e32 v2, 0xffffff7c, v116
	s_nop 0
	v_cndmask_b32_e32 v120, v141, v67, vcc
	v_cmp_lt_u32_e32 vcc, s21, v2
	v_add_u32_e32 v2, 0xffffff5c, v116
	s_nop 0
	v_cndmask_b32_e32 v64, v141, v52, vcc
	v_cmp_lt_u32_e32 vcc, s21, v2
	v_add_u32_e32 v2, 0xffffff7b, v116
	s_nop 0
	v_cndmask_b32_e32 v65, v141, v68, vcc
	v_cmp_lt_u32_e32 vcc, s21, v2
	v_add_u32_e32 v2, 0xffffff5b, v116
	s_nop 0
	v_cndmask_b32_e32 v66, v141, v53, vcc
	v_cmp_lt_u32_e32 vcc, s21, v2
	v_add_u32_e32 v2, 0xffffff7a, v116
	s_nop 0
	v_cndmask_b32_e32 v67, v141, v69, vcc
	v_cmp_lt_u32_e32 vcc, s21, v2
	v_add_u32_e32 v2, 0xffffff5a, v116
	s_nop 0
	v_cndmask_b32_e32 v52, v141, v54, vcc
	v_cmp_lt_u32_e32 vcc, s21, v2
	v_add_u32_e32 v2, 0xffffff79, v116
	s_nop 0
	v_cndmask_b32_e32 v53, v141, v70, vcc
	v_cmp_lt_u32_e32 vcc, s21, v2
	v_add_u32_e32 v2, 0xffffff59, v116
	s_nop 0
	v_cndmask_b32_e32 v54, v141, v55, vcc
	v_cmp_lt_u32_e32 vcc, s21, v2
	v_add_u32_e32 v2, 0xffffff70, v116
	s_nop 0
	v_cndmask_b32_e32 v55, v141, v71, vcc
	v_cmp_lt_u32_e32 vcc, s21, v2
	v_add_u32_e32 v2, 0xffffff50, v116
	s_nop 0
	v_cndmask_b32_e32 v48, v141, v56, vcc
	v_cmp_lt_u32_e32 vcc, s21, v2
	v_add_u32_e32 v2, 0xffffff6f, v116
	v_max_f32_e32 v56, v122, v122
	v_cndmask_b32_e32 v49, v141, v72, vcc
	v_cmp_lt_u32_e32 vcc, s21, v2
	v_add_u32_e32 v2, 0xffffff4f, v116
	v_max_f32_e32 v4, v56, v4
	v_cndmask_b32_e32 v50, v141, v57, vcc
	v_cmp_lt_u32_e32 vcc, s21, v2
	v_add_u32_e32 v2, 0xffffff6e, v116
	v_max_f32_e32 v56, v118, v118
	v_cndmask_b32_e32 v51, v141, v73, vcc
	v_cmp_lt_u32_e32 vcc, s21, v2
	v_max_f32_e32 v57, v117, v117
	v_max_f32_e32 v56, v57, v56
	v_cndmask_b32_e32 v12, v141, v58, vcc
	v_max_f32_e32 v57, v120, v120
	v_max_f32_e32 v58, v119, v119
	v_max3_f32 v4, v0, v121, v4
	v_max_f32_e32 v57, v58, v57
	v_max3_f32 v4, v4, v56, v57
	v_max_f32_e32 v56, v65, v65
	v_max_f32_e32 v57, v64, v64
	v_max_f32_e32 v56, v57, v56
	v_max_f32_e32 v57, v67, v67
	v_max_f32_e32 v58, v66, v66
	v_max_f32_e32 v57, v58, v57
	v_add_u32_e32 v2, 0xffffff4e, v116
	v_max3_f32 v4, v4, v56, v57
	v_max_f32_e32 v56, v53, v53
	v_max_f32_e32 v57, v52, v52
	v_cmp_lt_u32_e32 vcc, s21, v2
	v_add_u32_e32 v2, 0xffffff6d, v116
	v_max_f32_e32 v56, v57, v56
	v_max_f32_e32 v57, v55, v55
	v_max_f32_e32 v58, v54, v54
	v_cndmask_b32_e32 v13, v141, v74, vcc
	v_cmp_lt_u32_e32 vcc, s21, v2
	v_add_u32_e32 v2, 0xffffff4d, v116
	v_max_f32_e32 v57, v58, v57
	v_cndmask_b32_e32 v14, v141, v59, vcc
	v_cmp_lt_u32_e32 vcc, s21, v2
	v_add_u32_e32 v2, 0xffffff6c, v116
	v_max3_f32 v4, v4, v56, v57
	v_max_f32_e32 v56, v49, v49
	v_max_f32_e32 v57, v48, v48
	v_cndmask_b32_e32 v15, v141, v75, vcc
	v_cmp_lt_u32_e32 vcc, s21, v2
	v_add_u32_e32 v2, 0xffffff4c, v116
	v_max_f32_e32 v56, v57, v56
	v_max_f32_e32 v57, v51, v51
	v_max_f32_e32 v58, v50, v50
	v_cndmask_b32_e32 v8, v141, v60, vcc
	v_cmp_lt_u32_e32 vcc, s21, v2
	v_add_u32_e32 v2, 0xffffff6b, v116
	v_max_f32_e32 v57, v58, v57
	v_cndmask_b32_e32 v9, v141, v76, vcc
	v_cmp_lt_u32_e32 vcc, s21, v2
	v_add_u32_e32 v2, 0xffffff4b, v116
	v_max3_f32 v4, v4, v56, v57
	v_max_f32_e32 v56, v13, v13
	v_max_f32_e32 v57, v12, v12
	v_cndmask_b32_e32 v10, v141, v61, vcc
	v_cmp_lt_u32_e32 vcc, s21, v2
	v_add_u32_e32 v2, 0xffffff6a, v116
	v_max_f32_e32 v56, v57, v56
	v_max_f32_e32 v57, v15, v15
	v_max_f32_e32 v58, v14, v14
	v_cndmask_b32_e32 v11, v141, v77, vcc
	v_cmp_lt_u32_e32 vcc, s21, v2
	v_add_u32_e32 v2, 0xffffff4a, v116
	v_max_f32_e32 v57, v58, v57
	v_cndmask_b32_e32 v5, v141, v62, vcc
	v_cmp_lt_u32_e32 vcc, s21, v2
	v_add_u32_e32 v2, 0xffffff69, v116
	v_max3_f32 v4, v4, v56, v57
	v_max_f32_e32 v56, v9, v9
	v_max_f32_e32 v57, v8, v8
	v_cndmask_b32_e32 v6, v141, v78, vcc
	v_cmp_lt_u32_e32 vcc, s21, v2
	v_add_u32_e32 v2, 0xffffff49, v116
	v_max_f32_e32 v56, v57, v56
	v_max_f32_e32 v57, v11, v11
	v_max_f32_e32 v58, v10, v10
	v_cndmask_b32_e32 v7, v141, v63, vcc
	v_cmp_lt_u32_e32 vcc, s21, v2
	v_max_f32_e32 v57, v58, v57
	v_max3_f32 v4, v4, v56, v57
	v_cndmask_b32_e32 v2, v141, v79, vcc
	v_max_f32_e32 v56, v6, v6
	v_max_f32_e32 v57, v5, v5
	v_max_f32_e32 v56, v57, v56
	v_max_f32_e32 v57, v2, v2
	v_max_f32_e32 v58, v7, v7
	v_max_f32_e32 v57, v58, v57
	v_max3_f32 v4, v4, v56, v57
	v_mov_b32_e32 v56, v4
	s_nop 1
	v_permlane32_swap_b32_e32 v4, v56
	v_max3_f32 v4, v124, v4, v56
	v_cmp_gt_f32_e32 vcc, v4, v124
	s_cbranch_vccz .LBB0_461
; template <int NDB>
; __device__ __forceinline__ void sm_update(f32x16& s0, f32x16& s1, float& m, float& l, f32x16 (&o)[NDB], bf16x8 (&pk)[4]) {
;     ...
;         const float f = (mn > m) ? __builtin_amdgcn_exp2f(m - mn) : 1.f;
;         l *= f;
; #pragma unroll
;         for (int db = 0; db < NDB; ++db)
; #pragma unroll
;             for (int r = 0; r < 16; ++r) o[db][r] *= f;
;         m = mn;
	v_sub_f32_e32 v56, v124, v4
	v_exp_f32_e32 v56, v56
	s_nop 0
	v_cndmask_b32_e32 v56, 1.0, v56, vcc
	v_mul_f32_e32 v3, v3, v56
	v_pk_mul_f32 v[46:47], v[46:47], v[56:57] op_sel_hi:[1,0]
	v_pk_mul_f32 v[44:45], v[44:45], v[56:57] op_sel_hi:[1,0]
	v_pk_mul_f32 v[42:43], v[42:43], v[56:57] op_sel_hi:[1,0]
	v_pk_mul_f32 v[40:41], v[40:41], v[56:57] op_sel_hi:[1,0]
	v_pk_mul_f32 v[38:39], v[38:39], v[56:57] op_sel_hi:[1,0]
	v_pk_mul_f32 v[36:37], v[36:37], v[56:57] op_sel_hi:[1,0]
	v_pk_mul_f32 v[34:35], v[34:35], v[56:57] op_sel_hi:[1,0]
	v_pk_mul_f32 v[32:33], v[32:33], v[56:57] op_sel_hi:[1,0]
	v_pk_mul_f32 v[30:31], v[30:31], v[56:57] op_sel_hi:[1,0]
	v_pk_mul_f32 v[28:29], v[28:29], v[56:57] op_sel_hi:[1,0]
	v_pk_mul_f32 v[26:27], v[26:27], v[56:57] op_sel_hi:[1,0]
	v_pk_mul_f32 v[24:25], v[24:25], v[56:57] op_sel_hi:[1,0]
	v_pk_mul_f32 v[22:23], v[22:23], v[56:57] op_sel_hi:[1,0]
	v_pk_mul_f32 v[20:21], v[20:21], v[56:57] op_sel_hi:[1,0]
	v_pk_mul_f32 v[18:19], v[18:19], v[56:57] op_sel_hi:[1,0]
	v_pk_mul_f32 v[16:17], v[16:17], v[56:57] op_sel_hi:[1,0]
	s_branch .LBB0_462
